# phase_cmp_bias inner loop: all 32 (pe, w1) load pairs of a wave in flight, then the fma chain in the original order (was one pair per round trip)
# baseline (speedup 1.0000x reference)
.LBB0_519:
	s_waitcnt lgkmcnt(0)
	v_ashrrev_i32_e32 v8, 8, v2
	v_readlane_b32 s0, v236, 11
	v_ashrrev_i32_e32 v9, 31, v8
	v_readlane_b32 s1, v236, 12
	v_and_b32_e32 v3, 0xff, v0
	s_mov_b64 s[6:7], 0
	v_lshl_add_u64 v[10:11], s[0:1], 0, v[8:9]
	v_lshlrev_b64 v[8:9], 13, v[10:11]
	v_lshlrev_b64 v[10:11], 21, v[10:11]
	v_lshl_or_b32 v10, v3, 2, v10
	v_lshl_add_u64 v[8:9], v[4:5], 0, v[8:9]
	v_lshl_add_u64 v[10:11], v[6:7], 0, v[10:11]
	v_mov_b32_e32 v3, 0
	v_mov_b32_e32 v20, v18
	s_mov_b64 s[0:1], 0x10000
	global_load_dword v40, v[8:9], off
	global_load_dword v72, v[10:11], off
	v_lshl_add_u64 v[10:11], v[10:11], 0, s[0:1]
	global_load_dword v41, v[8:9], off offset:256
	global_load_dword v73, v[10:11], off
	v_lshl_add_u64 v[10:11], v[10:11], 0, s[0:1]
	global_load_dword v42, v[8:9], off offset:512
	global_load_dword v74, v[10:11], off
	v_lshl_add_u64 v[10:11], v[10:11], 0, s[0:1]
	global_load_dword v43, v[8:9], off offset:768
	global_load_dword v75, v[10:11], off
	v_lshl_add_u64 v[10:11], v[10:11], 0, s[0:1]
	global_load_dword v44, v[8:9], off offset:1024
	global_load_dword v76, v[10:11], off
	v_lshl_add_u64 v[10:11], v[10:11], 0, s[0:1]
	global_load_dword v45, v[8:9], off offset:1280
	global_load_dword v77, v[10:11], off
	v_lshl_add_u64 v[10:11], v[10:11], 0, s[0:1]
	global_load_dword v46, v[8:9], off offset:1536
	global_load_dword v78, v[10:11], off
	v_lshl_add_u64 v[10:11], v[10:11], 0, s[0:1]
	global_load_dword v47, v[8:9], off offset:1792
	global_load_dword v79, v[10:11], off
	v_lshl_add_u64 v[10:11], v[10:11], 0, s[0:1]
	global_load_dword v48, v[8:9], off offset:2048
	global_load_dword v80, v[10:11], off
	v_lshl_add_u64 v[10:11], v[10:11], 0, s[0:1]
	global_load_dword v49, v[8:9], off offset:2304
	global_load_dword v81, v[10:11], off
	v_lshl_add_u64 v[10:11], v[10:11], 0, s[0:1]
	global_load_dword v50, v[8:9], off offset:2560
	global_load_dword v82, v[10:11], off
	v_lshl_add_u64 v[10:11], v[10:11], 0, s[0:1]
	global_load_dword v51, v[8:9], off offset:2816
	global_load_dword v83, v[10:11], off
	v_lshl_add_u64 v[10:11], v[10:11], 0, s[0:1]
	global_load_dword v52, v[8:9], off offset:3072
	global_load_dword v84, v[10:11], off
	v_lshl_add_u64 v[10:11], v[10:11], 0, s[0:1]
	global_load_dword v53, v[8:9], off offset:3328
	global_load_dword v85, v[10:11], off
	v_lshl_add_u64 v[10:11], v[10:11], 0, s[0:1]
	global_load_dword v54, v[8:9], off offset:3584
	global_load_dword v86, v[10:11], off
	v_lshl_add_u64 v[10:11], v[10:11], 0, s[0:1]
	global_load_dword v55, v[8:9], off offset:3840
	global_load_dword v87, v[10:11], off
	v_lshl_add_u64 v[10:11], v[10:11], 0, s[0:1]
	s_mov_b64 s[6:7], 0x1000
	v_lshl_add_u64 v[8:9], v[8:9], 0, s[6:7]
	global_load_dword v56, v[8:9], off
	global_load_dword v88, v[10:11], off
	v_lshl_add_u64 v[10:11], v[10:11], 0, s[0:1]
	global_load_dword v57, v[8:9], off offset:256
	global_load_dword v89, v[10:11], off
	v_lshl_add_u64 v[10:11], v[10:11], 0, s[0:1]
	global_load_dword v58, v[8:9], off offset:512
	global_load_dword v90, v[10:11], off
	v_lshl_add_u64 v[10:11], v[10:11], 0, s[0:1]
	global_load_dword v59, v[8:9], off offset:768
	global_load_dword v91, v[10:11], off
	v_lshl_add_u64 v[10:11], v[10:11], 0, s[0:1]
	global_load_dword v60, v[8:9], off offset:1024
	global_load_dword v92, v[10:11], off
	v_lshl_add_u64 v[10:11], v[10:11], 0, s[0:1]
	global_load_dword v61, v[8:9], off offset:1280
	global_load_dword v93, v[10:11], off
	v_lshl_add_u64 v[10:11], v[10:11], 0, s[0:1]
	global_load_dword v62, v[8:9], off offset:1536
	global_load_dword v94, v[10:11], off
	v_lshl_add_u64 v[10:11], v[10:11], 0, s[0:1]
	global_load_dword v63, v[8:9], off offset:1792
	global_load_dword v95, v[10:11], off
	v_lshl_add_u64 v[10:11], v[10:11], 0, s[0:1]
	global_load_dword v64, v[8:9], off offset:2048
	global_load_dword v96, v[10:11], off
	v_lshl_add_u64 v[10:11], v[10:11], 0, s[0:1]
	global_load_dword v65, v[8:9], off offset:2304
	global_load_dword v97, v[10:11], off
	v_lshl_add_u64 v[10:11], v[10:11], 0, s[0:1]
	global_load_dword v66, v[8:9], off offset:2560
	global_load_dword v98, v[10:11], off
	v_lshl_add_u64 v[10:11], v[10:11], 0, s[0:1]
	global_load_dword v67, v[8:9], off offset:2816
	global_load_dword v99, v[10:11], off
	v_lshl_add_u64 v[10:11], v[10:11], 0, s[0:1]
	global_load_dword v68, v[8:9], off offset:3072
	global_load_dword v100, v[10:11], off
	v_lshl_add_u64 v[10:11], v[10:11], 0, s[0:1]
	global_load_dword v69, v[8:9], off offset:3328
	global_load_dword v101, v[10:11], off
	v_lshl_add_u64 v[10:11], v[10:11], 0, s[0:1]
	global_load_dword v70, v[8:9], off offset:3584
	global_load_dword v102, v[10:11], off
	v_lshl_add_u64 v[10:11], v[10:11], 0, s[0:1]
	global_load_dword v71, v[8:9], off offset:3840
	global_load_dword v103, v[10:11], off
	s_waitcnt vmcnt(62)
	v_fmac_f32_e32 v3, v40, v72
	s_waitcnt vmcnt(60)
	v_fmac_f32_e32 v3, v41, v73
	s_waitcnt vmcnt(58)
	v_fmac_f32_e32 v3, v42, v74
	s_waitcnt vmcnt(56)
	v_fmac_f32_e32 v3, v43, v75
	s_waitcnt vmcnt(54)
	v_fmac_f32_e32 v3, v44, v76
	s_waitcnt vmcnt(52)
	v_fmac_f32_e32 v3, v45, v77
	s_waitcnt vmcnt(50)
	v_fmac_f32_e32 v3, v46, v78
	s_waitcnt vmcnt(48)
	v_fmac_f32_e32 v3, v47, v79
	s_waitcnt vmcnt(46)
	v_fmac_f32_e32 v3, v48, v80
	s_waitcnt vmcnt(44)
	v_fmac_f32_e32 v3, v49, v81
	s_waitcnt vmcnt(42)
	v_fmac_f32_e32 v3, v50, v82
	s_waitcnt vmcnt(40)
	v_fmac_f32_e32 v3, v51, v83
	s_waitcnt vmcnt(38)
	v_fmac_f32_e32 v3, v52, v84
	s_waitcnt vmcnt(36)
	v_fmac_f32_e32 v3, v53, v85
	s_waitcnt vmcnt(34)
	v_fmac_f32_e32 v3, v54, v86
	s_waitcnt vmcnt(32)
	v_fmac_f32_e32 v3, v55, v87
	s_waitcnt vmcnt(30)
	v_fmac_f32_e32 v3, v56, v88
	s_waitcnt vmcnt(28)
	v_fmac_f32_e32 v3, v57, v89
	s_waitcnt vmcnt(26)
	v_fmac_f32_e32 v3, v58, v90
	s_waitcnt vmcnt(24)
	v_fmac_f32_e32 v3, v59, v91
	s_waitcnt vmcnt(22)
	v_fmac_f32_e32 v3, v60, v92
	s_waitcnt vmcnt(20)
	v_fmac_f32_e32 v3, v61, v93
	s_waitcnt vmcnt(18)
	v_fmac_f32_e32 v3, v62, v94
	s_waitcnt vmcnt(16)
	v_fmac_f32_e32 v3, v63, v95
	s_waitcnt vmcnt(14)
	v_fmac_f32_e32 v3, v64, v96
	s_waitcnt vmcnt(12)
	v_fmac_f32_e32 v3, v65, v97
	s_waitcnt vmcnt(10)
	v_fmac_f32_e32 v3, v66, v98
	s_waitcnt vmcnt(8)
	v_fmac_f32_e32 v3, v67, v99
	s_waitcnt vmcnt(6)
	v_fmac_f32_e32 v3, v68, v100
	s_waitcnt vmcnt(4)
	v_fmac_f32_e32 v3, v69, v101
	s_waitcnt vmcnt(2)
	v_fmac_f32_e32 v3, v70, v102
	s_waitcnt vmcnt(0)
	v_fmac_f32_e32 v3, v71, v103
	ds_bpermute_b32 v8, v12, v3
	s_waitcnt lgkmcnt(0)
	v_add_f32_e32 v3, v3, v8
	ds_bpermute_b32 v8, v13, v3
	s_waitcnt lgkmcnt(0)
	v_add_f32_e32 v3, v3, v8
	ds_bpermute_b32 v8, v14, v3
	s_waitcnt lgkmcnt(0)
	v_add_f32_e32 v3, v3, v8
	ds_bpermute_b32 v8, v15, v3
	s_waitcnt lgkmcnt(0)
	v_add_f32_e32 v3, v3, v8
	ds_bpermute_b32 v8, v16, v3
	s_waitcnt lgkmcnt(0)
	v_add_f32_e32 v3, v3, v8
	ds_bpermute_b32 v8, v17, v3
	s_and_saveexec_b64 s[0:1], vcc
	s_cbranch_execz .LBB0_518
	v_readlane_b32 s8, v237, 57
	s_waitcnt lgkmcnt(0)
	v_add_f32_e32 v10, v3, v8
	v_ashrrev_i32_e32 v3, 31, v2
	v_readlane_b32 s14, v237, 63
	v_readlane_b32 s15, v236, 0
	v_readlane_b32 s9, v237, 58
	v_readlane_b32 s10, v237, 59
	v_lshl_add_u64 v[8:9], v[2:3], 2, s[14:15]
	v_readlane_b32 s11, v237, 60
	v_readlane_b32 s12, v237, 61
	v_readlane_b32 s13, v237, 62
	global_store_dword v[8:9], v10, off
	s_branch .LBB0_518
